# slot fusion v2: layer-1 table conversion overlapped with phase-6 GEMMs (CU mates convert before/after their tile); empty slot barrier removed
# speedup vs baseline: 1.0090x; 1.0090x over previous
; DEVI unsigned xb_add(unsigned* p, unsigned v) { return __hip_atomic_fetch_add(p, v, __ATOMIC_RELAXED, __HIP_MEMORY_SCOPE_AGENT); }
; #define GSYNC xcd_barrier(bar, xcc, nloc, nx)
; DEVI void xcd_barrier(unsigned* bar, unsigned x, unsigned nloc, unsigned nx) {
;   asm volatile("s_waitcnt vmcnt(0)" ::: "memory");
;   __syncthreads();
;   if (threadIdx.x == 0) {
;     __builtin_amdgcn_s_waitcnt(0);
;     const unsigned old = xb_add(&bar[XB_XSUB(x)], 1u);
;     const unsigned gen = old / nloc;
;     if (old + 1u == (gen + 1u) * nloc) {
;       __builtin_amdgcn_fence(__ATOMIC_RELEASE, "agent");
;       asm volatile("s_waitcnt vmcnt(0)" ::: "memory");
;       const unsigned og = xb_add(&bar[XB_TOP], 1u);
;       const unsigned tg = og / nx;
;       if (og + 1u == (tg + 1u) * nx) xb_add(&bar[XB_TOPGEN], 1u);
; __global__ void __launch_bounds__(256, 2) fwd_megakernel(Params P) {
;     ...
;       if (!(l == 1 && it == 2)) GSYNC;
.LBB0_298:
	s_xor_b64 s[42:43], s[72:73], -1
	s_mov_b64 s[72:73], 0
	s_mov_b64 s[40:41], -1
	s_and_b64 vcc, exec, s[42:43]
	s_cbranch_vccz .Lsplit_latch
	v_readlane_b32 s4, v252, 34
	s_cmp_lg_u32 s0, s0
	v_readlane_b32 s5, v252, 35
	s_cselect_b64 s[40:41], -1, 0
	s_xor_b64 s[42:43], s[4:5], -1
	s_or_b64 s[40:41], s[42:43], s[40:41]
	s_and_b64 vcc, exec, s[40:41]
	v_readlane_b32 s74, v252, 32
	s_cbranch_vccz .LBB0_338
	s_waitcnt vmcnt(0)
	s_barrier
	s_mov_b64 s[40:41], exec
	v_readlane_b32 s42, v253, 4
	v_readlane_b32 s43, v253, 5
	s_and_b64 s[42:43], s[40:41], s[42:43]
	s_mov_b64 exec, s[42:43]
	s_cbranch_execz .LBB0_337
	s_mov_b64 s[42:43], exec
	v_mbcnt_lo_u32_b32 v0, s42, 0
	v_mbcnt_hi_u32_b32 v0, s43, v0
	v_cmp_eq_u32_e32 vcc, 0, v0
	s_waitcnt vmcnt(0) expcnt(0) lgkmcnt(0)
	s_and_saveexec_b64 s[44:45], vcc
	s_cbranch_execz .LBB0_303
	s_bcnt1_i32_b64 s1, s[42:43]
	v_readlane_b32 s4, v253, 30
	v_mov_b32_e32 v1, s1
	v_readlane_b32 s5, v253, 31
	s_nop 4
	global_atomic_add v1, v89, v1, s[4:5] sc0

; DEVI char* wsp(const Params& P, size_t off) { asm volatile("" : "+s"(off)); return P.ws + off; }
; DEVI int ltid() { int t = threadIdx.x; asm volatile("" : "+v"(t)); return t; }
; DEVI void convert_chunk_fp8(const float* __restrict__ src, unsigned char* __restrict__ dst, float scale, int tid) {
;   int o = tid * 16;
;   uint4 r;
;   unsigned rr[4];
; #pragma unroll
;   for (int q = 0; q < 4; ++q) {
;     float4 a = *reinterpret_cast<const float4*>(src + o + q * 4);
;     int p = __builtin_amdgcn_cvt_pk_fp8_f32(a.x * scale, a.y * scale, 0, false);
;     p = __builtin_amdgcn_cvt_pk_fp8_f32(a.z * scale, a.w * scale, p, true);
;     rr[q] = (unsigned)p;
;   }
;   r = make_uint4(rr[0], rr[1], rr[2], rr[3]);
;   *reinterpret_cast<uint4*>(dst + o) = r;
; }
; DEVI void phase6(const Params& P, int l, int pass, char* smem) {
;   const int tid = ltid();
;   const int ntok = pass ? 8192 : 8448;
;   const int nM = ntok / 128, nN = 8;
;   const bfu* Z = (const bfu*)wsp(P, O_Z);
;   bfu* M = (bfu*)wsp(P, O_CB);
;   for (int id = blockIdx.x; id < nM * nN; id += gridDim.x) {
;     int pm, pn; tile_rc_m(id, nM, nN, pm, pn);
;     float* macc = (float*)wsp(P, O_AU);
;     p6_branch<2, 1, 1>(P, pm, pn, macc, smem, tid);
;     p6_branch<1, 2, 0>(P, pm, pn, macc, smem, tid);
;   }
; }
.LBB0_728:
	s_or_b64 exec, exec, s[26:27]
	s_barrier
	s_cmp_lg_u32 s0, 1
	s_cbranch_scc1 .Ltb_skip_a
	s_cmp_lg_u32 s90, 0
	s_cbranch_scc1 .Ltb_skip_a
	s_cmpk_lt_u32 s74, 0x100
	s_cbranch_scc0 .Ltb_skip_a
	v_readlane_b32 s54, v253, 22
	v_readlane_b32 s55, v253, 23
	v_readlane_b32 s56, v253, 24
	v_readlane_b32 s57, v253, 25
	s_add_u32 s54, s54, 0x4000000
	s_addc_u32 s55, s55, 0
	s_add_u32 s56, s56, 0x4000000
	s_addc_u32 s57, s57, 0
	v_lshlrev_b32_e32 v248, 6, v93
	v_lshlrev_b32_e32 v250, 4, v93
	v_mov_b32_e32 v251, 0
	v_lshl_add_u64 v[250:251], v[64:65], 0, v[250:251]
	s_mov_b32 s1, s74
.Ltb_loop_a:
	s_lshl_b32 s2, s1, 14
	s_add_u32 s42, s54, s2
	s_addc_u32 s43, s55, 0
	s_add_u32 s44, s56, s2
	s_addc_u32 s45, s57, 0
	global_load_dwordx4 v[208:211], v248, s[42:43]
	global_load_dwordx4 v[212:215], v248, s[42:43] offset:16
	global_load_dwordx4 v[216:219], v248, s[42:43] offset:32
	global_load_dwordx4 v[220:223], v248, s[42:43] offset:48
	global_load_dwordx4 v[224:227], v248, s[44:45]
	global_load_dwordx4 v[228:231], v248, s[44:45] offset:16
	global_load_dwordx4 v[232:235], v248, s[44:45] offset:32
	global_load_dwordx4 v[236:239], v248, s[44:45] offset:48
	s_lshl_b32 s2, s1, 12
	s_add_u32 s58, s2, 0x2500000
	s_mov_b32 s59, 0
	v_lshl_add_u64 v[202:203], v[250:251], 0, s[58:59]
	s_add_u32 s58, s2, 0x4500000
	v_lshl_add_u64 v[204:205], v[250:251], 0, s[58:59]
	s_waitcnt vmcnt(4)
	v_mul_f32_e32 v208, 0x42800000, v208
	v_mul_f32_e32 v209, 0x42800000, v209
	v_mul_f32_e32 v210, 0x42800000, v210
	v_mul_f32_e32 v211, 0x42800000, v211
	v_mul_f32_e32 v212, 0x42800000, v212
	v_mul_f32_e32 v213, 0x42800000, v213
	v_mul_f32_e32 v214, 0x42800000, v214
	v_mul_f32_e32 v215, 0x42800000, v215
	v_mul_f32_e32 v216, 0x42800000, v216
	v_mul_f32_e32 v217, 0x42800000, v217
	v_mul_f32_e32 v218, 0x42800000, v218
	v_mul_f32_e32 v219, 0x42800000, v219
	v_mul_f32_e32 v220, 0x42800000, v220
	v_mul_f32_e32 v221, 0x42800000, v221
	v_mul_f32_e32 v222, 0x42800000, v222
	v_mul_f32_e32 v223, 0x42800000, v223
	v_mov_b32_e32 v240, v89
	v_mov_b32_e32 v241, v89
	v_mov_b32_e32 v242, v89
	v_mov_b32_e32 v243, v89
	v_cvt_pk_fp8_f32 v240, v208, v209
	v_cvt_pk_fp8_f32 v241, v212, v213
	v_cvt_pk_fp8_f32 v242, v216, v217
	v_cvt_pk_fp8_f32 v243, v220, v221
	v_cvt_pk_fp8_f32 v240, v210, v211 op_sel:[0,0,1]
	v_cvt_pk_fp8_f32 v241, v214, v215 op_sel:[0,0,1]
	v_cvt_pk_fp8_f32 v242, v218, v219 op_sel:[0,0,1]
	v_cvt_pk_fp8_f32 v243, v222, v223 op_sel:[0,0,1]
	global_store_dwordx4 v[202:203], v[240:243], off
	s_waitcnt vmcnt(1)
	v_mul_f32_e32 v224, 0x41000000, v224
	v_mul_f32_e32 v225, 0x41000000, v225
	v_mul_f32_e32 v226, 0x41000000, v226
	v_mul_f32_e32 v227, 0x41000000, v227
	v_mul_f32_e32 v228, 0x41000000, v228
	v_mul_f32_e32 v229, 0x41000000, v229
	v_mul_f32_e32 v230, 0x41000000, v230
	v_mul_f32_e32 v231, 0x41000000, v231
	v_mul_f32_e32 v232, 0x41000000, v232
	v_mul_f32_e32 v233, 0x41000000, v233
	v_mul_f32_e32 v234, 0x41000000, v234
	v_mul_f32_e32 v235, 0x41000000, v235
	v_mul_f32_e32 v236, 0x41000000, v236
	v_mul_f32_e32 v237, 0x41000000, v237
	v_mul_f32_e32 v238, 0x41000000, v238
	v_mul_f32_e32 v239, 0x41000000, v239
	v_mov_b32_e32 v244, v89
	v_mov_b32_e32 v245, v89
	v_mov_b32_e32 v246, v89
	v_mov_b32_e32 v247, v89
	v_cvt_pk_fp8_f32 v244, v224, v225
	v_cvt_pk_fp8_f32 v245, v228, v229
	v_cvt_pk_fp8_f32 v246, v232, v233
	v_cvt_pk_fp8_f32 v247, v236, v237
	v_cvt_pk_fp8_f32 v244, v226, v227 op_sel:[0,0,1]
	v_cvt_pk_fp8_f32 v245, v230, v231 op_sel:[0,0,1]
	v_cvt_pk_fp8_f32 v246, v234, v235 op_sel:[0,0,1]
	v_cvt_pk_fp8_f32 v247, v238, v239 op_sel:[0,0,1]
	global_store_dwordx4 v[204:205], v[244:247], off
	s_addk_i32 s1, 0x200
	s_cmpk_lt_u32 s1, 0x1000
	s_cbranch_scc1 .Ltb_loop_a
.Ltb_skip_a:
	v_mov_b32_e32 v91, v93
	s_cmp_eq_u32 s90, 0
	s_movk_i32 s1, 0x210
	s_mov_b64 s[26:27], 0x8582000
	s_cselect_b32 s1, s1, 0x200
	s_mov_b64 s[26:27], 0x17d02000
	s_cmp_ge_i32 s74, s1
	s_cbranch_scc1 .LBB0_743
	v_ashrrev_i32_e32 v0, 3, v91
	v_lshlrev_b32_e32 v101, 4, v91
	v_xor_b32_e32 v4, v0, v91
	v_lshlrev_b32_e32 v4, 3, v4
	v_add_u32_e32 v103, 0x1000, v101
	v_and_b32_e32 v100, 56, v4
	v_ashrrev_i32_e32 v4, 7, v103
	v_xor_b32_e32 v8, v4, v91
	v_lshlrev_b32_e32 v8, 3, v8
	v_add_u32_e32 v105, 0x2000, v101
	v_and_b32_e32 v102, 56, v8
	v_ashrrev_i32_e32 v8, 7, v105
	v_xor_b32_e32 v12, v8, v91
	v_lshrrev_b32_e32 v16, 4, v91
	v_lshlrev_b32_e32 v12, 3, v12
	v_add_u32_e32 v107, 0x3000, v101
	v_and_b32_e32 v20, 7, v91
	v_and_b32_e32 v104, 56, v12
	v_ashrrev_i32_e32 v12, 7, v107
	v_bitop3_b32 v16, v16, v20, 3 bitop3:0x6c
	v_bfe_u32 v17, v91, 4, 2
	v_xor_b32_e32 v18, v12, v91
	v_lshlrev_b32_e32 v146, 4, v16
	v_lshlrev_b32_e32 v16, 7, v91
	v_lshlrev_b32_e32 v18, 3, v18
	v_and_b32_e32 v148, 0x2780, v16
	v_bitop3_b32 v16, v17, v20, 4 bitop3:0x36
	v_and_b32_e32 v106, 56, v18
	v_and_b32_e32 v18, 15, v91
	v_lshrrev_b32_e32 v19, 1, v91
	s_mov_b32 s2, 0x1ffffc0
	v_lshlrev_b32_e32 v149, 4, v16
	v_lshrrev_b32_e32 v16, 2, v91
	v_and_or_b32 v18, v19, s2, v18
	v_and_b32_e32 v16, 12, v16
	s_mov_b32 s2, 0x7fffc0
	v_and_or_b32 v16, v19, s2, v16
	v_and_b32_e32 v17, 0x4f, v91
	v_lshlrev_b32_e32 v16, 9, v16
	v_ashrrev_i32_e32 v1, 31, v0
	v_lshl_or_b32 v150, v17, 2, v16
	v_lshlrev_b32_e32 v16, 2, v91
	v_lshlrev_b64 v[2:3], 10, v[0:1]
	v_ashrrev_i32_e32 v5, 31, v4
	v_and_b32_e32 v151, 0x7c, v16
	v_lshlrev_b64 v[16:17], 11, v[0:1]
	v_bitop3_b32 v0, v0, 7, v91 bitop3:0x48
	v_lshlrev_b64 v[6:7], 10, v[4:5]
	v_lshl_or_b32 v16, v0, 4, v16
	v_readlane_b32 s4, v252, 25
	v_lshlrev_b64 v[0:1], 11, v[4:5]
	v_bitop3_b32 v4, v4, 7, v91 bitop3:0x48
	v_ashrrev_i32_e32 v9, 31, v8
	v_readlane_b32 s5, v252, 26
	v_lshl_or_b32 v0, v4, 4, v0
	v_bitop3_b32 v4, v8, 7, v91 bitop3:0x48
	v_lshl_add_u64 v[110:111], s[4:5], 0, v[0:1]
	v_lshlrev_b64 v[0:1], 11, v[8:9]
	v_ashrrev_i32_e32 v13, 31, v12
	v_lshl_or_b32 v0, v4, 4, v0
	v_lshl_add_u64 v[112:113], s[4:5], 0, v[0:1]
	v_lshlrev_b64 v[0:1], 11, v[12:13]
	v_bitop3_b32 v4, v12, 7, v91 bitop3:0x48
	v_lshlrev_b64 v[10:11], 10, v[8:9]
	v_lshlrev_b64 v[14:15], 10, v[12:13]
	v_lshl_or_b32 v0, v4, 4, v0
	v_lshlrev_b32_e32 v147, 7, v18
	v_lshlrev_b32_e32 v152, 2, v151
	v_lshl_add_u64 v[108:109], s[4:5], 0, v[16:17]
	v_lshl_add_u64 v[114:115], s[4:5], 0, v[0:1]
	v_lshlrev_b64 v[116:117], 1, v[2:3]
	v_lshlrev_b64 v[118:119], 1, v[6:7]
	v_lshlrev_b64 v[120:121], 1, v[10:11]
	v_lshlrev_b64 v[122:123], 1, v[14:15]
	s_mov_b32 s2, s74

; DEVI char* wsp(const Params& P, size_t off) { asm volatile("" : "+s"(off)); return P.ws + off; }
; DEVI int ltid() { int t = threadIdx.x; asm volatile("" : "+v"(t)); return t; }
; DEVI void convert_chunk_fp8(const float* __restrict__ src, unsigned char* __restrict__ dst, float scale, int tid) {
;   int o = tid * 16;
;   uint4 r;
;   unsigned rr[4];
; #pragma unroll
;   for (int q = 0; q < 4; ++q) {
;     float4 a = *reinterpret_cast<const float4*>(src + o + q * 4);
;     int p = __builtin_amdgcn_cvt_pk_fp8_f32(a.x * scale, a.y * scale, 0, false);
;     p = __builtin_amdgcn_cvt_pk_fp8_f32(a.z * scale, a.w * scale, p, true);
;     rr[q] = (unsigned)p;
;   }
;   r = make_uint4(rr[0], rr[1], rr[2], rr[3]);
;   *reinterpret_cast<uint4*>(dst + o) = r;
; }
; DEVI void phase6(const Params& P, int l, int pass, char* smem) {
;   const int tid = ltid();
;   const int ntok = pass ? 8192 : 8448;
;   const int nM = ntok / 128, nN = 8;
;   const bfu* Z = (const bfu*)wsp(P, O_Z);
;   bfu* M = (bfu*)wsp(P, O_CB);
;   for (int id = blockIdx.x; id < nM * nN; id += gridDim.x) {
;     int pm, pn; tile_rc_m(id, nM, nN, pm, pn);
;     float* macc = (float*)wsp(P, O_AU);
;     p6_branch<2, 1, 1>(P, pm, pn, macc, smem, tid);
;     p6_branch<1, 2, 0>(P, pm, pn, macc, smem, tid);
;   }
; }
.LBB0_743:
	s_cmp_lg_u32 s0, 1
	s_cbranch_scc1 .Ltb_skip_b
	s_cmp_lg_u32 s90, 0
	s_cbranch_scc1 .Ltb_skip_b
	s_cmpk_lt_u32 s74, 0x100
	s_cbranch_scc1 .Ltb_skip_b
	v_readlane_b32 s54, v253, 22
	v_readlane_b32 s55, v253, 23
	v_readlane_b32 s56, v253, 24
	v_readlane_b32 s57, v253, 25
	s_add_u32 s54, s54, 0x4000000
	s_addc_u32 s55, s55, 0
	s_add_u32 s56, s56, 0x4000000
	s_addc_u32 s57, s57, 0
	v_lshlrev_b32_e32 v248, 6, v93
	v_lshlrev_b32_e32 v250, 4, v93
	v_mov_b32_e32 v251, 0
	v_lshl_add_u64 v[250:251], v[64:65], 0, v[250:251]
	s_mov_b32 s1, s74
